# v2 + s_setprio 3 for the rwkv/ssd scan units (pole waves win VALU arbitration over co-resident conv/lru/ret waves)
# speedup vs baseline: 1.0008x; 1.0008x over previous
; __device__ __forceinline__ void run_phase(CP p, int ph, char* smem_full) {
;     ...
;     case 3: {
;       for (int u = vb; u < 320; u += NVB) {
;         if (u < 128) { for (int rr_ = 0; rr_ < ((SCAN_REP >> 0) & 1) + 1; ++rr_) rwkv_scan_unit(p, u, smem); }
;         else if (u < 256) { for (int rr_ = 0; rr_ < ((SCAN_REP >> 1) & 1) + 1; ++rr_) ssd_scan_unit(p, l, u - 128, smem); }
;         else if (u < 272) ret_mfma_unit(p, l, u - 256, smem);
;         else if (u < 288) { }
;         else if (u < 320) { for (int rr_ = 0; rr_ < ((SCAN_REP >> 3) & 1) + 1; ++rr_) lru_scan_unit(p, u - 288, smem); }
;       }
.LBB0_394:
	s_setprio 0
	v_readlane_b32 s0, v253, 45
	s_add_i32 s57, s57, s6
	s_add_i32 s37, s37, s0
	s_cmpk_gt_i32 s57, 0x13f
	s_cbranch_scc1 .LBB0_586

; __device__ __forceinline__ int tidx() { int t = threadIdx.x & 255; asm volatile("" : "+v"(t)); return t; }
; __device__ __forceinline__ int half_id() { int t = (int)(threadIdx.x >> 8); asm volatile("" : "+v"(t)); return __builtin_amdgcn_readfirstlane(t); }
; #define LAS3 __attribute__((address_space(3)))
; __device__ __forceinline__ void half_barrier(char* smem_half) {
;   const int h = half_id();
;   LAS3 unsigned* cnt = (LAS3 unsigned*)(smem_half + (2 - h) * 65536 + 8 + h * 4);
;   asm volatile("s_waitcnt lgkmcnt(0)" ::: "memory");
;   if ((tidx() & 63) == 0) {
;     const unsigned old = __hip_atomic_fetch_add(cnt, 1u, __ATOMIC_RELAXED, __HIP_MEMORY_SCOPE_WORKGROUP);
;     const unsigned target = (old & ~3u) + 4u;
;     while (__hip_atomic_load(cnt, __ATOMIC_RELAXED, __HIP_MEMORY_SCOPE_WORKGROUP) < target) __builtin_amdgcn_s_sleep(1);
;   }
; __device__ __forceinline__ void ssd_scan_unit(CP p, int l, int u, char* smem) {
;     ...
;   const int b = u >> 4, h = (u >> 2) & 3, q = u & 3, g = h >> 1;
;   const int prow = wid * 4 + i;
;   const bf16_t* SS = (const bf16_t*)(p.ws + WS_SS);
;   const float* SD = (const float*)(p.ws + WS_SD);
;   bf16_t* Y = (bf16_t*)(p.ws + WS_Y);
;   const float Ah = -__expf(p.in[11][l * 4 + h]);
;   const float Dh = p.in[12][l * 4 + h];
.LBB0_527:
	s_andn2_b64 vcc, exec, s[2:3]
	s_movk_i32 s0, 0x600
	s_mov_b32 s54, s59
	v_readlane_b32 s55, v254, 9
	s_cbranch_vccnz .LBB0_558
	s_setprio 3
	s_add_i32 s11, s57, 0xffffff80
	s_bfe_u32 s28, s11, 0x20002
	v_readlane_b32 s1, v254, 11
	s_or_b32 s2, s28, s1
	s_ashr_i32 s3, s2, 31
	s_lshl_b64 s[2:3], s[2:3], 2
	v_readlane_b32 s12, v254, 14
	v_readlane_b32 s13, v254, 15
	s_add_u32 s4, s12, s2
	v_readlane_b32 s14, v254, 16
	s_addc_u32 s5, s13, s3
	v_readlane_b32 s15, v254, 17
	s_add_u32 s2, s14, s2
	s_waitcnt vmcnt(0)
	v_mov_b32_e32 v12, v214
	s_addc_u32 s3, s15, s3
	global_load_dword v0, v149, s[4:5]
	s_waitcnt lgkmcnt(1)
	global_load_dword v43, v149, s[2:3]
	v_mov_b32_e32 v1, v213
	s_waitcnt lgkmcnt(0)
	s_nop 0
	v_readfirstlane_b32 s12, v1
	v_mov_b32_e32 v1, v214
	s_nop 0
	v_and_b32_e32 v1, 63, v1
	v_cmp_eq_u32_e32 vcc, 0, v1
	s_and_saveexec_b64 s[2:3], vcc
	s_cbranch_execz .LBB0_534
	s_mov_b64 s[4:5], exec
	s_lshl_b32 s10, s12, 16
	v_mbcnt_lo_u32_b32 v1, s4, 0
	s_sub_i32 s10, s63, s10
	v_mbcnt_hi_u32_b32 v1, s5, v1
	s_add_i32 s10, s10, 0x20000
	s_lshl_b32 s29, s12, 2
	v_cmp_eq_u32_e32 vcc, 0, v1
	s_and_saveexec_b64 s[12:13], vcc
	s_bcnt1_i32_b64 s4, s[4:5]
	s_add_i32 s5, s10, s29
	v_mov_b32_e32 v2, s5
	v_mov_b32_e32 v3, s4
	ds_add_rtn_u32 v2, v2, v3 offset:8
	s_or_b64 exec, exec, s[12:13]
	s_add_i32 s10, s10, s29
	s_waitcnt lgkmcnt(0)
	v_readfirstlane_b32 s4, v2
	v_mov_b32_e32 v2, s10
	ds_read_b32 v2, v2 offset:8
	v_add_u32_e32 v1, s4, v1
	v_and_b32_e32 v1, -4, v1
	v_add_u32_e32 v1, 4, v1
	s_waitcnt lgkmcnt(0)
	v_cmp_lt_u32_e32 vcc, v2, v1
	s_and_b64 exec, exec, vcc
	s_cbranch_execz .LBB0_534
	s_mov_b64 s[4:5], 0

; __device__ __forceinline__ int tidx() { int t = threadIdx.x & 255; asm volatile("" : "+v"(t)); return t; }
; __device__ __forceinline__ int half_id() { int t = (int)(threadIdx.x >> 8); asm volatile("" : "+v"(t)); return __builtin_amdgcn_readfirstlane(t); }
; #define LAS3 __attribute__((address_space(3)))
; __device__ __forceinline__ void half_barrier(char* smem_half) {
;   const int h = half_id();
;   LAS3 unsigned* cnt = (LAS3 unsigned*)(smem_half + (2 - h) * 65536 + 8 + h * 4);
;   asm volatile("s_waitcnt lgkmcnt(0)" ::: "memory");
;   if ((tidx() & 63) == 0) {
;     const unsigned old = __hip_atomic_fetch_add(cnt, 1u, __ATOMIC_RELAXED, __HIP_MEMORY_SCOPE_WORKGROUP);
;     const unsigned target = (old & ~3u) + 4u;
;     while (__hip_atomic_load(cnt, __ATOMIC_RELAXED, __HIP_MEMORY_SCOPE_WORKGROUP) < target) __builtin_amdgcn_s_sleep(1);
;   }
; __device__ __forceinline__ void rwkv_scan_unit(CP p, int u, char* smem) {
;   float* buf = (float*)smem;
;   const int tid = tidx(), wid = tid >> 6, lane = tid & 63, i = lane >> 4, j = lane & 15;
.LBB0_559:
	s_andn2_b64 vcc, exec, s[2:3]
	s_cbranch_vccnz .LBB0_394
	s_setprio 3
	s_waitcnt vmcnt(2)
	v_mov_b32_e32 v22, v214
	v_mov_b32_e32 v0, v213
	s_waitcnt lgkmcnt(0)
	s_nop 0
	v_readfirstlane_b32 s11, v0
	v_mov_b32_e32 v0, v214
	s_nop 0
	v_and_b32_e32 v0, 63, v0
	v_cmp_eq_u32_e32 vcc, 0, v0
	s_and_saveexec_b64 s[2:3], vcc
	s_cbranch_execz .LBB0_566
	s_mov_b64 s[4:5], exec
	s_lshl_b32 s10, s11, 16
	v_mbcnt_lo_u32_b32 v0, s4, 0
	s_sub_i32 s10, s63, s10
	v_mbcnt_hi_u32_b32 v0, s5, v0
	s_add_i32 s10, s10, 0x20000
	s_lshl_b32 s11, s11, 2
	v_cmp_eq_u32_e32 vcc, 0, v0
	s_and_saveexec_b64 s[12:13], vcc
	s_bcnt1_i32_b64 s4, s[4:5]
	s_add_i32 s5, s10, s11
	v_mov_b32_e32 v1, s5
	v_mov_b32_e32 v2, s4
	ds_add_rtn_u32 v1, v1, v2 offset:8
	s_or_b64 exec, exec, s[12:13]
	s_add_i32 s10, s10, s11
	s_waitcnt lgkmcnt(0)
	v_readfirstlane_b32 s4, v1
	v_mov_b32_e32 v1, s10
	ds_read_b32 v1, v1 offset:8
	v_add_u32_e32 v0, s4, v0
	v_and_b32_e32 v0, -4, v0
	v_add_u32_e32 v0, 4, v0
	s_waitcnt lgkmcnt(0)
	v_cmp_lt_u32_e32 vcc, v1, v0
	s_and_b64 exec, exec, vcc
	s_cbranch_execz .LBB0_566
	s_mov_b64 s[4:5], 0
